# in_proj barrier shadow: the 64 memKV workgroups (critical path) skip their deferred-transpose step; 64 one-piece workgroups run a second step covering those tiles
# baseline (speedup 1.0000x reference)
.Lbar_wait:
	v_readlane_b32 s10, v254, 62
	s_cmpk_lg_u32 s10, 0x100
	s_cbranch_scc1 .Lbs_no0
	s_cmp_eq_u32 s70, 1
	s_cbranch_scc1 .Lbs_c0
	s_cmp_lg_u32 s70, 2
	s_cbranch_scc1 .Lbs_no0
	s_branch .Lbs_no0_y
.Lbs_c0:
	v_readlane_b32 s10, v255, 2
	s_sub_i32 s10, s10, 0x9c
	s_cmpk_lt_u32 s10, 0x40
	s_cbranch_scc1 .Lbs_no0

.Lbs_again:
	v_readlane_b32 s0, v254, 56
	v_readlane_b32 s1, v254, 57
	s_load_dwordx2 s[18:19], s[0:1], 0x108
	v_ashrrev_i32_e32 v1, 4, v174
	s_waitcnt vmcnt(0) lgkmcnt(0)

.Ltb_end:
	s_mov_b64 exec, -1
	s_cmp_lg_u32 s70, 1
	s_cbranch_scc1 .Ltb_fin
	v_readlane_b32 s0, v143, 0
	s_sub_i32 s0, s0, 0x8c0
	s_cmpk_lt_u32 s0, 0x40
	s_cbranch_scc0 .Ltb_fin
	s_add_i32 s0, s0, 0x91c
	s_movk_i32 s32, 0xc80
	v_mov_b32_e32 v143, s0
	s_branch .Lbs_again
